# context DFT: VC rows prefetched three groups ahead (ring of 4), twiddle address via one VALU add, unpack skewed between multiply and adds
# speedup vs baseline: 1.0285x; 1.0042x over previous
; __device__ __forceinline__ void fft1_phase(KP P, int l) {
;     ...
;         const unsigned* VC = (const unsigned*)(ws + WS_VC); bf16_t* OM = (bf16_t*)(ws + WS_XN);
;         for (int gt = bid_ * 512 + tid_; gt < NB * CTXL * 256; gt += gridDim.x * 512) {
;             const int ch = gt & 255, k = (gt >> 8) & 255, b = gt >> 16;
;             const unsigned* vp = VC + (size_t)(b * 256) * 256 + ch; float a = 0.f;
; #pragma unroll 8
;             for (int j = 0; j < 256; ++j) { const unsigned pk = vp[(size_t)j * 256]; const float vr = __uint_as_float(pk << 16), vi = __uint_as_float(pk & 0xffff0000u);
;                 const int ix = ((k * j) & 255) * 32; a += vr * TAB[TAB_COS + ix] + vi * TAB[TAB_COS + ((ix - 2048) & 8191)]; }
.LBB0_47:
	v_readfirstlane_b32 s20, v9
	v_add_co_u32_e32 v20, vcc, 0xb100000, v4
	s_and_b32 s20, s20, 0xff
	s_nop 1
	v_addc_co_u32_e32 v21, vcc, 0, v5, vcc
	s_lshl_b32 s20, s20, 3
	v_add_co_u32_e32 v22, vcc, 0x1000, v20
	s_mov_b32 s21, 0
	s_nop 1
	v_addc_co_u32_e32 v23, vcc, 0, v21, vcc
	v_mov_b32_e32 v25, 0x1e000
	s_mov_b32 s2, 8
	global_load_dword v32, v[20:21], off offset:0
	global_load_dword v33, v[20:21], off offset:1024
	global_load_dword v34, v[20:21], off offset:2048
	global_load_dword v35, v[20:21], off offset:3072
	global_load_dword v36, v[22:23], off offset:0
	global_load_dword v37, v[22:23], off offset:1024
	global_load_dword v38, v[22:23], off offset:2048
	global_load_dword v39, v[22:23], off offset:3072
	v_add_co_u32_e32 v20, vcc, 0x2000, v20
	s_nop 1
	v_addc_co_u32_e32 v21, vcc, 0, v21, vcc
	v_add_co_u32_e32 v22, vcc, 0x2000, v22
	s_nop 1
	v_addc_co_u32_e32 v23, vcc, 0, v23, vcc
	global_load_dword v40, v[20:21], off offset:0
	global_load_dword v41, v[20:21], off offset:1024
	global_load_dword v42, v[20:21], off offset:2048
	global_load_dword v43, v[20:21], off offset:3072
	global_load_dword v44, v[22:23], off offset:0
	global_load_dword v45, v[22:23], off offset:1024
	global_load_dword v46, v[22:23], off offset:2048
	global_load_dword v47, v[22:23], off offset:3072
	v_add_co_u32_e32 v20, vcc, 0x2000, v20
	s_nop 1
	v_addc_co_u32_e32 v21, vcc, 0, v21, vcc
	v_add_co_u32_e32 v22, vcc, 0x2000, v22
	s_nop 1
	v_addc_co_u32_e32 v23, vcc, 0, v23, vcc
	global_load_dword v80, v[20:21], off offset:0
	global_load_dword v81, v[20:21], off offset:1024
	global_load_dword v82, v[20:21], off offset:2048
	global_load_dword v83, v[20:21], off offset:3072
	global_load_dword v84, v[22:23], off offset:0
	global_load_dword v85, v[22:23], off offset:1024
	global_load_dword v86, v[22:23], off offset:2048
	global_load_dword v87, v[22:23], off offset:3072
	v_add_co_u32_e32 v20, vcc, 0x2000, v20
	s_nop 1
	v_addc_co_u32_e32 v21, vcc, 0, v21, vcc
	v_add_co_u32_e32 v22, vcc, 0x2000, v22
	s_nop 1
	v_addc_co_u32_e32 v23, vcc, 0, v23, vcc
	v_add_u32_e32 v24, s21, v25
	s_add_i32 s21, s21, s20
	ds_read_b64 v[48:49], v24
	s_and_b32 s21, s21, 0x7f8
	v_add_u32_e32 v24, s21, v25
	s_add_i32 s21, s21, s20
	ds_read_b64 v[50:51], v24
	s_and_b32 s21, s21, 0x7f8
	v_add_u32_e32 v24, s21, v25
	s_add_i32 s21, s21, s20
	ds_read_b64 v[52:53], v24
	s_and_b32 s21, s21, 0x7f8
	v_add_u32_e32 v24, s21, v25
	s_add_i32 s21, s21, s20
	ds_read_b64 v[54:55], v24
	s_and_b32 s21, s21, 0x7f8
	v_add_u32_e32 v24, s21, v25
	s_add_i32 s21, s21, s20
	ds_read_b64 v[56:57], v24
	s_and_b32 s21, s21, 0x7f8
	v_add_u32_e32 v24, s21, v25
	s_add_i32 s21, s21, s20
	ds_read_b64 v[58:59], v24
	s_and_b32 s21, s21, 0x7f8
	v_add_u32_e32 v24, s21, v25
	s_add_i32 s21, s21, s20
	ds_read_b64 v[60:61], v24
	s_and_b32 s21, s21, 0x7f8
	v_add_u32_e32 v24, s21, v25
	s_add_i32 s21, s21, s20
	ds_read_b64 v[62:63], v24
	s_and_b32 s21, s21, 0x7f8
.Lcd_loop:
	global_load_dword v88, v[20:21], off offset:0
	global_load_dword v89, v[20:21], off offset:1024
	global_load_dword v90, v[20:21], off offset:2048
	global_load_dword v91, v[20:21], off offset:3072
	global_load_dword v92, v[22:23], off offset:0
	global_load_dword v93, v[22:23], off offset:1024
	global_load_dword v94, v[22:23], off offset:2048
	global_load_dword v95, v[22:23], off offset:3072
	v_add_co_u32_e32 v20, vcc, 0x2000, v20
	s_nop 1
	v_addc_co_u32_e32 v21, vcc, 0, v21, vcc
	v_add_co_u32_e32 v22, vcc, 0x2000, v22
	s_nop 1
	v_addc_co_u32_e32 v23, vcc, 0, v23, vcc
	v_add_u32_e32 v24, s21, v25
	s_add_i32 s21, s21, s20
	ds_read_b64 v[64:65], v24
	s_and_b32 s21, s21, 0x7f8
	v_add_u32_e32 v24, s21, v25
	s_add_i32 s21, s21, s20
	ds_read_b64 v[66:67], v24
	s_and_b32 s21, s21, 0x7f8
	v_add_u32_e32 v24, s21, v25
	s_add_i32 s21, s21, s20
	ds_read_b64 v[68:69], v24
	s_and_b32 s21, s21, 0x7f8
	v_add_u32_e32 v24, s21, v25
	s_add_i32 s21, s21, s20
	ds_read_b64 v[70:71], v24
	s_and_b32 s21, s21, 0x7f8
	v_add_u32_e32 v24, s21, v25
	s_add_i32 s21, s21, s20
	ds_read_b64 v[72:73], v24
	s_and_b32 s21, s21, 0x7f8
	v_add_u32_e32 v24, s21, v25
	s_add_i32 s21, s21, s20
	ds_read_b64 v[74:75], v24
	s_and_b32 s21, s21, 0x7f8
	v_add_u32_e32 v24, s21, v25
	s_add_i32 s21, s21, s20
	ds_read_b64 v[76:77], v24
	s_and_b32 s21, s21, 0x7f8
	v_add_u32_e32 v24, s21, v25
	s_add_i32 s21, s21, s20
	ds_read_b64 v[78:79], v24
	s_and_b32 s21, s21, 0x7f8
	s_waitcnt vmcnt(24) lgkmcnt(8)
; __device__ __forceinline__ void fft1_phase(KP P, int l) {
;     ...
; #pragma unroll 8
;             for (int j = 0; j < 256; ++j) { const unsigned pk = vp[(size_t)j * 256]; const float vr = __uint_as_float(pk << 16), vi = __uint_as_float(pk & 0xffff0000u);
;                 const int ix = ((k * j) & 255) * 32; a += vr * TAB[TAB_COS + ix] + vi * TAB[TAB_COS + ((ix - 2048) & 8191)]; }
	v_lshlrev_b32_e32 v26, 16, v32
	v_and_b32_e32 v27, 0xffff0000, v32
	v_pk_mul_f32 v[26:27], v[48:49], v[26:27]
	v_lshlrev_b32_e32 v28, 16, v33
	v_and_b32_e32 v29, 0xffff0000, v33
	v_add_f32_e32 v26, v26, v27
	v_add_f32_e32 v19, v19, v26
	v_pk_mul_f32 v[28:29], v[50:51], v[28:29]
	v_lshlrev_b32_e32 v26, 16, v34
	v_and_b32_e32 v27, 0xffff0000, v34
	v_add_f32_e32 v28, v28, v29
	v_add_f32_e32 v19, v19, v28
	v_pk_mul_f32 v[26:27], v[52:53], v[26:27]
	v_lshlrev_b32_e32 v28, 16, v35
	v_and_b32_e32 v29, 0xffff0000, v35
	v_add_f32_e32 v26, v26, v27
	v_add_f32_e32 v19, v19, v26
	v_pk_mul_f32 v[28:29], v[54:55], v[28:29]
	v_lshlrev_b32_e32 v26, 16, v36
	v_and_b32_e32 v27, 0xffff0000, v36
	v_add_f32_e32 v28, v28, v29
	v_add_f32_e32 v19, v19, v28
	v_pk_mul_f32 v[26:27], v[56:57], v[26:27]
	v_lshlrev_b32_e32 v28, 16, v37
	v_and_b32_e32 v29, 0xffff0000, v37
	v_add_f32_e32 v26, v26, v27
	v_add_f32_e32 v19, v19, v26
	v_pk_mul_f32 v[28:29], v[58:59], v[28:29]
	v_lshlrev_b32_e32 v26, 16, v38
	v_and_b32_e32 v27, 0xffff0000, v38
	v_add_f32_e32 v28, v28, v29
	v_add_f32_e32 v19, v19, v28
	v_pk_mul_f32 v[26:27], v[60:61], v[26:27]
	v_lshlrev_b32_e32 v28, 16, v39
	v_and_b32_e32 v29, 0xffff0000, v39
	v_add_f32_e32 v26, v26, v27
	v_add_f32_e32 v19, v19, v26
	v_pk_mul_f32 v[28:29], v[62:63], v[28:29]
	s_nop 0
	v_add_f32_e32 v28, v28, v29
	v_add_f32_e32 v19, v19, v28
	global_load_dword v32, v[20:21], off offset:0
	global_load_dword v33, v[20:21], off offset:1024
	global_load_dword v34, v[20:21], off offset:2048
	global_load_dword v35, v[20:21], off offset:3072
	global_load_dword v36, v[22:23], off offset:0
	global_load_dword v37, v[22:23], off offset:1024
	global_load_dword v38, v[22:23], off offset:2048
	global_load_dword v39, v[22:23], off offset:3072
	v_add_co_u32_e32 v20, vcc, 0x2000, v20
	s_nop 1
	v_addc_co_u32_e32 v21, vcc, 0, v21, vcc
	v_add_co_u32_e32 v22, vcc, 0x2000, v22
	s_nop 1
	v_addc_co_u32_e32 v23, vcc, 0, v23, vcc
	v_add_u32_e32 v24, s21, v25
	s_add_i32 s21, s21, s20
	ds_read_b64 v[48:49], v24
	s_and_b32 s21, s21, 0x7f8
	v_add_u32_e32 v24, s21, v25
	s_add_i32 s21, s21, s20
	ds_read_b64 v[50:51], v24
	s_and_b32 s21, s21, 0x7f8
	v_add_u32_e32 v24, s21, v25
	s_add_i32 s21, s21, s20
	ds_read_b64 v[52:53], v24
	s_and_b32 s21, s21, 0x7f8
	v_add_u32_e32 v24, s21, v25
	s_add_i32 s21, s21, s20
	ds_read_b64 v[54:55], v24
	s_and_b32 s21, s21, 0x7f8
	v_add_u32_e32 v24, s21, v25
	s_add_i32 s21, s21, s20
	ds_read_b64 v[56:57], v24
	s_and_b32 s21, s21, 0x7f8
	v_add_u32_e32 v24, s21, v25
	s_add_i32 s21, s21, s20
	ds_read_b64 v[58:59], v24
	s_and_b32 s21, s21, 0x7f8
	v_add_u32_e32 v24, s21, v25
	s_add_i32 s21, s21, s20
	ds_read_b64 v[60:61], v24
	s_and_b32 s21, s21, 0x7f8
	v_add_u32_e32 v24, s21, v25
	s_add_i32 s21, s21, s20
	ds_read_b64 v[62:63], v24
	s_and_b32 s21, s21, 0x7f8
	s_waitcnt vmcnt(24) lgkmcnt(8)
	v_lshlrev_b32_e32 v26, 16, v40
	v_and_b32_e32 v27, 0xffff0000, v40
	v_pk_mul_f32 v[26:27], v[64:65], v[26:27]
	v_lshlrev_b32_e32 v28, 16, v41
	v_and_b32_e32 v29, 0xffff0000, v41
	v_add_f32_e32 v26, v26, v27
	v_add_f32_e32 v19, v19, v26
	v_pk_mul_f32 v[28:29], v[66:67], v[28:29]
	v_lshlrev_b32_e32 v26, 16, v42
	v_and_b32_e32 v27, 0xffff0000, v42
	v_add_f32_e32 v28, v28, v29
	v_add_f32_e32 v19, v19, v28
	v_pk_mul_f32 v[26:27], v[68:69], v[26:27]
	v_lshlrev_b32_e32 v28, 16, v43
	v_and_b32_e32 v29, 0xffff0000, v43
	v_add_f32_e32 v26, v26, v27
	v_add_f32_e32 v19, v19, v26
	v_pk_mul_f32 v[28:29], v[70:71], v[28:29]
	v_lshlrev_b32_e32 v26, 16, v44
	v_and_b32_e32 v27, 0xffff0000, v44
	v_add_f32_e32 v28, v28, v29
	v_add_f32_e32 v19, v19, v28
	v_pk_mul_f32 v[26:27], v[72:73], v[26:27]
	v_lshlrev_b32_e32 v28, 16, v45
	v_and_b32_e32 v29, 0xffff0000, v45
	v_add_f32_e32 v26, v26, v27
	v_add_f32_e32 v19, v19, v26
	v_pk_mul_f32 v[28:29], v[74:75], v[28:29]
	v_lshlrev_b32_e32 v26, 16, v46
	v_and_b32_e32 v27, 0xffff0000, v46
	v_add_f32_e32 v28, v28, v29
	v_add_f32_e32 v19, v19, v28
	v_pk_mul_f32 v[26:27], v[76:77], v[26:27]
	v_lshlrev_b32_e32 v28, 16, v47
	v_and_b32_e32 v29, 0xffff0000, v47
	v_add_f32_e32 v26, v26, v27
	v_add_f32_e32 v19, v19, v26
	v_pk_mul_f32 v[28:29], v[78:79], v[28:29]
	s_nop 0
	v_add_f32_e32 v28, v28, v29
	v_add_f32_e32 v19, v19, v28
	global_load_dword v40, v[20:21], off offset:0
	global_load_dword v41, v[20:21], off offset:1024
	global_load_dword v42, v[20:21], off offset:2048
	global_load_dword v43, v[20:21], off offset:3072
	global_load_dword v44, v[22:23], off offset:0
	global_load_dword v45, v[22:23], off offset:1024
	global_load_dword v46, v[22:23], off offset:2048
	global_load_dword v47, v[22:23], off offset:3072
	v_add_co_u32_e32 v20, vcc, 0x2000, v20
	s_nop 1
	v_addc_co_u32_e32 v21, vcc, 0, v21, vcc
	v_add_co_u32_e32 v22, vcc, 0x2000, v22
	s_nop 1
	v_addc_co_u32_e32 v23, vcc, 0, v23, vcc
	v_add_u32_e32 v24, s21, v25
	s_add_i32 s21, s21, s20
	ds_read_b64 v[64:65], v24
	s_and_b32 s21, s21, 0x7f8
	v_add_u32_e32 v24, s21, v25
	s_add_i32 s21, s21, s20
	ds_read_b64 v[66:67], v24
	s_and_b32 s21, s21, 0x7f8
	v_add_u32_e32 v24, s21, v25
	s_add_i32 s21, s21, s20
	ds_read_b64 v[68:69], v24
	s_and_b32 s21, s21, 0x7f8
	v_add_u32_e32 v24, s21, v25
	s_add_i32 s21, s21, s20
	ds_read_b64 v[70:71], v24
	s_and_b32 s21, s21, 0x7f8
	v_add_u32_e32 v24, s21, v25
	s_add_i32 s21, s21, s20
	ds_read_b64 v[72:73], v24
	s_and_b32 s21, s21, 0x7f8
	v_add_u32_e32 v24, s21, v25
	s_add_i32 s21, s21, s20
	ds_read_b64 v[74:75], v24
	s_and_b32 s21, s21, 0x7f8
	v_add_u32_e32 v24, s21, v25
	s_add_i32 s21, s21, s20
	ds_read_b64 v[76:77], v24
	s_and_b32 s21, s21, 0x7f8
	v_add_u32_e32 v24, s21, v25
	s_add_i32 s21, s21, s20
	ds_read_b64 v[78:79], v24
	s_and_b32 s21, s21, 0x7f8
	s_waitcnt vmcnt(24) lgkmcnt(8)
; __device__ __forceinline__ bf16_t f2bf(float f) { unsigned u = __float_as_uint(f); return (bf16_t)((u + 0x7fffu + ((u >> 16) & 1u)) >> 16); }
; __device__ __forceinline__ void fft1_phase(KP P, int l) {
;     ...
;             for (int j = 0; j < 256; ++j) { const unsigned pk = vp[(size_t)j * 256]; const float vr = __uint_as_float(pk << 16), vi = __uint_as_float(pk & 0xffff0000u);
;                 const int ix = ((k * j) & 255) * 32; a += vr * TAB[TAB_COS + ix] + vi * TAB[TAB_COS + ((ix - 2048) & 8191)]; }
;             OM[(size_t)(b * RPB + SEQ + k) * DM + 768 + ch] = f2bf(a * (1.f / 128.f));
;         }
	v_lshlrev_b32_e32 v26, 16, v80
	v_and_b32_e32 v27, 0xffff0000, v80
	v_pk_mul_f32 v[26:27], v[48:49], v[26:27]
	v_lshlrev_b32_e32 v28, 16, v81
	v_and_b32_e32 v29, 0xffff0000, v81
	v_add_f32_e32 v26, v26, v27
	v_add_f32_e32 v19, v19, v26
	v_pk_mul_f32 v[28:29], v[50:51], v[28:29]
	v_lshlrev_b32_e32 v26, 16, v82
	v_and_b32_e32 v27, 0xffff0000, v82
	v_add_f32_e32 v28, v28, v29
	v_add_f32_e32 v19, v19, v28
	v_pk_mul_f32 v[26:27], v[52:53], v[26:27]
	v_lshlrev_b32_e32 v28, 16, v83
	v_and_b32_e32 v29, 0xffff0000, v83
	v_add_f32_e32 v26, v26, v27
	v_add_f32_e32 v19, v19, v26
	v_pk_mul_f32 v[28:29], v[54:55], v[28:29]
	v_lshlrev_b32_e32 v26, 16, v84
	v_and_b32_e32 v27, 0xffff0000, v84
	v_add_f32_e32 v28, v28, v29
	v_add_f32_e32 v19, v19, v28
	v_pk_mul_f32 v[26:27], v[56:57], v[26:27]
	v_lshlrev_b32_e32 v28, 16, v85
	v_and_b32_e32 v29, 0xffff0000, v85
	v_add_f32_e32 v26, v26, v27
	v_add_f32_e32 v19, v19, v26
	v_pk_mul_f32 v[28:29], v[58:59], v[28:29]
	v_lshlrev_b32_e32 v26, 16, v86
	v_and_b32_e32 v27, 0xffff0000, v86
	v_add_f32_e32 v28, v28, v29
	v_add_f32_e32 v19, v19, v28
	v_pk_mul_f32 v[26:27], v[60:61], v[26:27]
	v_lshlrev_b32_e32 v28, 16, v87
	v_and_b32_e32 v29, 0xffff0000, v87
	v_add_f32_e32 v26, v26, v27
	v_add_f32_e32 v19, v19, v26
	v_pk_mul_f32 v[28:29], v[62:63], v[28:29]
	s_nop 0
	v_add_f32_e32 v28, v28, v29
	v_add_f32_e32 v19, v19, v28
	global_load_dword v80, v[20:21], off offset:0
	global_load_dword v81, v[20:21], off offset:1024
	global_load_dword v82, v[20:21], off offset:2048
	global_load_dword v83, v[20:21], off offset:3072
	global_load_dword v84, v[22:23], off offset:0
	global_load_dword v85, v[22:23], off offset:1024
	global_load_dword v86, v[22:23], off offset:2048
	global_load_dword v87, v[22:23], off offset:3072
	v_add_co_u32_e32 v20, vcc, 0x2000, v20
	s_nop 1
	v_addc_co_u32_e32 v21, vcc, 0, v21, vcc
	v_add_co_u32_e32 v22, vcc, 0x2000, v22
	s_nop 1
	v_addc_co_u32_e32 v23, vcc, 0, v23, vcc
	v_add_u32_e32 v24, s21, v25
	s_add_i32 s21, s21, s20
	ds_read_b64 v[48:49], v24
	s_and_b32 s21, s21, 0x7f8
	v_add_u32_e32 v24, s21, v25
	s_add_i32 s21, s21, s20
	ds_read_b64 v[50:51], v24
	s_and_b32 s21, s21, 0x7f8
	v_add_u32_e32 v24, s21, v25
	s_add_i32 s21, s21, s20
	ds_read_b64 v[52:53], v24
	s_and_b32 s21, s21, 0x7f8
	v_add_u32_e32 v24, s21, v25
	s_add_i32 s21, s21, s20
	ds_read_b64 v[54:55], v24
	s_and_b32 s21, s21, 0x7f8
	v_add_u32_e32 v24, s21, v25
	s_add_i32 s21, s21, s20
	ds_read_b64 v[56:57], v24
	s_and_b32 s21, s21, 0x7f8
	v_add_u32_e32 v24, s21, v25
	s_add_i32 s21, s21, s20
	ds_read_b64 v[58:59], v24
	s_and_b32 s21, s21, 0x7f8
	v_add_u32_e32 v24, s21, v25
	s_add_i32 s21, s21, s20
	ds_read_b64 v[60:61], v24
	s_and_b32 s21, s21, 0x7f8
	v_add_u32_e32 v24, s21, v25
	s_add_i32 s21, s21, s20
	ds_read_b64 v[62:63], v24
	s_and_b32 s21, s21, 0x7f8
	s_waitcnt vmcnt(24) lgkmcnt(8)
	v_lshlrev_b32_e32 v26, 16, v88
	v_and_b32_e32 v27, 0xffff0000, v88
	v_pk_mul_f32 v[26:27], v[64:65], v[26:27]
	v_lshlrev_b32_e32 v28, 16, v89
	v_and_b32_e32 v29, 0xffff0000, v89
	v_add_f32_e32 v26, v26, v27
	v_add_f32_e32 v19, v19, v26
	v_pk_mul_f32 v[28:29], v[66:67], v[28:29]
	v_lshlrev_b32_e32 v26, 16, v90
	v_and_b32_e32 v27, 0xffff0000, v90
	v_add_f32_e32 v28, v28, v29
	v_add_f32_e32 v19, v19, v28
	v_pk_mul_f32 v[26:27], v[68:69], v[26:27]
	v_lshlrev_b32_e32 v28, 16, v91
	v_and_b32_e32 v29, 0xffff0000, v91
	v_add_f32_e32 v26, v26, v27
	v_add_f32_e32 v19, v19, v26
	v_pk_mul_f32 v[28:29], v[70:71], v[28:29]
	v_lshlrev_b32_e32 v26, 16, v92
	v_and_b32_e32 v27, 0xffff0000, v92
	v_add_f32_e32 v28, v28, v29
	v_add_f32_e32 v19, v19, v28
	v_pk_mul_f32 v[26:27], v[72:73], v[26:27]
	v_lshlrev_b32_e32 v28, 16, v93
	v_and_b32_e32 v29, 0xffff0000, v93
	v_add_f32_e32 v26, v26, v27
	v_add_f32_e32 v19, v19, v26
	v_pk_mul_f32 v[28:29], v[74:75], v[28:29]
	v_lshlrev_b32_e32 v26, 16, v94
	v_and_b32_e32 v27, 0xffff0000, v94
	v_add_f32_e32 v28, v28, v29
	v_add_f32_e32 v19, v19, v28
	v_pk_mul_f32 v[26:27], v[76:77], v[26:27]
	v_lshlrev_b32_e32 v28, 16, v95
	v_and_b32_e32 v29, 0xffff0000, v95
	v_add_f32_e32 v26, v26, v27
	v_add_f32_e32 v19, v19, v26
	v_pk_mul_f32 v[28:29], v[78:79], v[28:29]
	s_nop 0
	v_add_f32_e32 v28, v28, v29
	v_add_f32_e32 v19, v19, v28
	s_sub_u32 s2, s2, 1
	s_cmp_lg_u32 s2, 0
	s_cbranch_scc1 .Lcd_loop
	s_waitcnt vmcnt(0) lgkmcnt(0)
	v_mul_f32_e32 v4, 0x3c000000, v19
	v_bfe_u32 v5, v4, 16, 1
	v_add3_u32 v6, v4, v5, s44
	v_mul_i32_i24_sdwa v4, sext(v8), s81 dst_sel:DWORD dst_unused:UNUSED_PAD src0_sel:WORD_1 src1_sel:DWORD
	v_and_or_b32 v4, v9, s36, v4
	v_add_u32_e32 v4, 0x2000, v4
	v_ashrrev_i32_e32 v5, 31, v4
	v_add_u32_e32 v8, s0, v8
	s_mov_b32 s2, 0x1ffff
	v_lshlrev_b64 v[4:5], 11, v[4:5]
	v_cmp_lt_i32_e32 vcc, s2, v8
	v_lshl_add_u64 v[4:5], v[0:1], 0, v[4:5]
	s_or_b64 s[14:15], vcc, s[14:15]
	global_store_short_d16_hi v[4:5], v6, off
	s_andn2_b64 exec, exec, s[14:15]
	s_cbranch_execnz .LBB0_46
